# attention loops: s_setprio 1 around QK and PV MFMA clusters (co-resident wave runs softmax VALU under them)
# speedup vs baseline: 1.0229x; 1.0005x over previous
.LBB0_1021:
	s_bitcmp1_b32 s0, 0
	s_cselect_b32 s0, 0x8800, 0
	s_add_i32 s87, s0, 0
	s_cmp_ge_i32 s5, s28
	s_cbranch_scc1 .LBB0_1107
	s_cmp_lt_i32 s5, s7
	s_cselect_b64 s[0:1], -1, 0
	s_cmp_ge_i32 s5, s7
	s_cselect_b64 s[2:3], -1, 0
	s_add_i32 s20, s4, s5
	s_add_i32 s20, s20, -4
	v_cmp_ge_u32_e64 s[58:59], s20, v200
	v_cmp_lt_u32_e32 vcc, s20, v201
	s_and_b64 s[56:57], s[58:59], vcc
	s_or_b64 s[56:57], s[2:3], s[56:57]
	s_and_saveexec_b64 s[2:3], s[56:57]
	s_cbranch_execz .LBB0_1102
	v_add_u32_e32 v0, s87, v202
	v_add_u32_e32 v76, v0, v203
	v_add_u32_e32 v0, v0, v204
	ds_read_b128 v[108:111], v76
	ds_read_b128 v[112:115], v76 offset:2048
	ds_read_b128 v[116:119], v76 offset:4096
	ds_read_b128 v[120:123], v76 offset:6144
	ds_read_b128 v[124:127], v0
	ds_read_b128 v[128:131], v0 offset:2048
	ds_read_b128 v[132:135], v0 offset:4096
	ds_read_b128 v[136:139], v0 offset:6144
	v_add3_u32 v0, s87, v199, v205
	v_add_u32_e32 v92, 0x2000, v0
	v_add_u32_e32 v96, 0x2800, v0
	v_add_u32_e32 v100, 0x3000, v0
	v_add_u32_e32 v0, 0x3800, v0
	ds_read2_b64 v[76:79], v92 offset1:4
	ds_read2_b64 v[80:83], v96 offset0:32 offset1:36
	ds_read2_b64 v[84:87], v100 offset0:64 offset1:68
	ds_read2_b64 v[88:91], v0 offset0:96 offset1:100
	ds_read2_b64 v[92:95], v92 offset0:8 offset1:12
	ds_read2_b64 v[96:99], v96 offset0:40 offset1:44
	ds_read2_b64 v[100:103], v100 offset0:72 offset1:76
	ds_read2_b64 v[104:107], v0 offset0:104 offset1:108
	s_waitcnt lgkmcnt(14)
	s_setprio 1
	v_mfma_f32_16x16x32_bf16 v[140:143], v[108:111], v[4:7], 0
	v_mfma_f32_16x16x32_bf16 v[108:111], v[108:111], v[12:15], 0
	v_mfma_f32_16x16x32_bf16 v[144:147], v[112:115], v[4:7], 0
	v_mfma_f32_16x16x32_bf16 v[112:115], v[112:115], v[12:15], 0
	s_waitcnt lgkmcnt(13)
	v_mfma_f32_16x16x32_bf16 v[148:151], v[116:119], v[4:7], 0
	v_mfma_f32_16x16x32_bf16 v[116:119], v[116:119], v[12:15], 0
	s_waitcnt lgkmcnt(12)
	v_mfma_f32_16x16x32_bf16 v[152:155], v[120:123], v[4:7], 0
	v_mfma_f32_16x16x32_bf16 v[120:123], v[120:123], v[12:15], 0
	s_waitcnt lgkmcnt(11)
	v_mfma_f32_16x16x32_bf16 v[140:143], v[124:127], v[8:11], v[140:143]
	v_mfma_f32_16x16x32_bf16 v[108:111], v[124:127], v[16:19], v[108:111]
	s_waitcnt lgkmcnt(10)
	v_mfma_f32_16x16x32_bf16 v[144:147], v[128:131], v[8:11], v[144:147]
	v_mfma_f32_16x16x32_bf16 v[112:115], v[128:131], v[16:19], v[112:115]
	s_waitcnt lgkmcnt(9)
	v_mfma_f32_16x16x32_bf16 v[148:151], v[132:135], v[8:11], v[148:151]
	v_mfma_f32_16x16x32_bf16 v[116:119], v[132:135], v[16:19], v[116:119]
	s_waitcnt lgkmcnt(8)
	v_mfma_f32_16x16x32_bf16 v[152:155], v[136:139], v[8:11], v[152:155]
	v_mfma_f32_16x16x32_bf16 v[120:123], v[136:139], v[16:19], v[120:123]
	s_setprio 0
	v_cndmask_b32_e64 v0, 0, 1, s[0:1]
	v_cmp_ne_u32_e64 s[56:57], 1, v0
	s_andn2_b64 vcc, exec, s[0:1]
	s_mov_b64 s[66:67], -1
	s_cbranch_vccnz .LBB0_1189
	v_add3_u32 v0, v225, s5, -4
	v_max_i32_e32 v0, -7, v0
	v_add_u32_e32 v0, 7, v0
	v_readlane_b32 s65, v254, 35
	v_cmp_lt_u32_e32 vcc, s20, v206
	v_min_u32_e32 v0, 14, v0
	v_mov_b32_e32 v124, s65
	s_movk_i32 s65, 0x7c
	v_mad_u32_u24 v0, v0, s65, v124
	v_lshl_add_u32 v124, v207, 2, v0
	v_lshl_add_u32 v125, v208, 2, v0
	v_lshl_add_u32 v126, v209, 2, v0
	v_lshl_add_u32 v127, v210, 2, v0
	v_lshl_add_u32 v128, v211, 2, v0
	v_lshl_add_u32 v129, v212, 2, v0
	v_lshl_add_u32 v130, v213, 2, v0
	v_lshl_add_u32 v131, v214, 2, v0
	v_lshl_add_u32 v132, v215, 2, v0
	v_lshl_add_u32 v133, v216, 2, v0
	v_lshl_add_u32 v134, v217, 2, v0
	v_lshl_add_u32 v135, v218, 2, v0
	v_lshl_add_u32 v136, v219, 2, v0
	v_lshl_add_u32 v137, v220, 2, v0
	v_lshl_add_u32 v138, v221, 2, v0
	v_lshl_add_u32 v139, v222, 2, v0
	ds_read_b32 v124, v124 offset:60
	ds_read_b32 v125, v125 offset:60
	ds_read_b32 v126, v126 offset:60
	ds_read_b32 v127, v127 offset:60
	ds_read_b32 v128, v128
	ds_read_b32 v129, v129
	ds_read_b32 v130, v130
	ds_read_b32 v131, v131
	ds_read_b32 v132, v132
	ds_read_b32 v133, v133
	ds_read_b32 v134, v134
	ds_read_b32 v135, v135
	ds_read_b32 v136, v136
	ds_read_b32 v137, v137
	ds_read_b32 v138, v138
	ds_read_b32 v139, v139
	s_and_b64 s[58:59], s[58:59], vcc
	v_mov_b32_e32 v0, 0xff800000
	s_and_b64 s[66:67], s[40:41], s[58:59]
	s_waitcnt lgkmcnt(0)
	v_fmac_f32_e32 v124, 0x3e38aa3b, v140
	v_fmac_f32_e32 v125, 0x3e38aa3b, v141
	v_fmac_f32_e32 v126, 0x3e38aa3b, v142
	v_fmac_f32_e32 v127, 0x3e38aa3b, v143
	v_fmac_f32_e32 v128, 0x3e38aa3b, v144
	v_fmac_f32_e32 v129, 0x3e38aa3b, v145
	v_fmac_f32_e32 v130, 0x3e38aa3b, v146
	v_fmac_f32_e32 v131, 0x3e38aa3b, v147
	v_fmac_f32_e32 v132, 0x3e38aa3b, v148
	v_fmac_f32_e32 v133, 0x3e38aa3b, v149
	v_fmac_f32_e32 v134, 0x3e38aa3b, v150
	v_fmac_f32_e32 v135, 0x3e38aa3b, v151
	v_fmac_f32_e32 v136, 0x3e38aa3b, v152
	v_fmac_f32_e32 v137, 0x3e38aa3b, v153
	v_fmac_f32_e32 v138, 0x3e38aa3b, v154
	v_fmac_f32_e32 v139, 0x3e38aa3b, v155
	s_and_b64 s[82:83], s[42:43], s[58:59]
	v_cndmask_b32_e64 v124, v0, v124, s[66:67]
	s_and_b64 s[66:67], s[44:45], s[58:59]
	v_cndmask_b32_e64 v125, v0, v125, s[82:83]
	s_and_b64 s[82:83], s[46:47], s[58:59]
	v_cndmask_b32_e64 v126, v0, v126, s[66:67]
	s_and_b64 s[66:67], s[90:91], s[58:59]
	v_cndmask_b32_e64 v127, v0, v127, s[82:83]
	s_and_b64 s[82:83], s[8:9], s[58:59]
	v_cndmask_b32_e64 v128, v0, v128, s[66:67]
	s_and_b64 s[66:67], s[88:89], s[58:59]
	v_cndmask_b32_e64 v129, v0, v129, s[82:83]
	s_and_b64 s[82:83], s[94:95], s[58:59]
	v_cndmask_b32_e64 v130, v0, v130, s[66:67]
	s_and_b64 s[66:67], s[96:97], s[58:59]
	v_cndmask_b32_e64 v131, v0, v131, s[82:83]
	s_and_b64 s[82:83], s[84:85], s[58:59]
	v_cndmask_b32_e64 v132, v0, v132, s[66:67]
	s_and_b64 s[66:67], s[18:19], s[58:59]
	v_cndmask_b32_e64 v133, v0, v133, s[82:83]
	s_and_b64 s[82:83], s[62:63], s[58:59]
	v_cndmask_b32_e64 v134, v0, v134, s[66:67]
	s_and_b64 s[66:67], s[48:49], s[58:59]
	v_cndmask_b32_e64 v135, v0, v135, s[82:83]
	s_and_b64 s[82:83], s[50:51], s[58:59]
	v_cndmask_b32_e64 v136, v0, v136, s[66:67]
	s_and_b64 s[66:67], s[52:53], s[58:59]
	v_cndmask_b32_e64 v137, v0, v137, s[82:83]
	s_and_b64 s[82:83], s[54:55], s[58:59]
	v_cndmask_b32_e64 v138, v0, v138, s[66:67]
	s_nop 0
	v_cndmask_b32_e64 v139, v0, v139, s[82:83]
	v_max3_f32 v0, v2, v124, v125
	v_max3_f32 v0, v0, v126, v127
	v_max3_f32 v0, v0, v128, v129
	v_max3_f32 v0, v0, v130, v131
	v_max3_f32 v0, v0, v132, v133
	v_max3_f32 v0, v0, v134, v135
	v_max3_f32 v0, v0, v136, v137
	v_max3_f32 v0, v0, v138, v139

.LBB0_1101:
	s_mov_b32 s66, s64
	s_mov_b32 s67, s64
	v_cvt_pk_bf16_f32 v108, v108, v109
	v_cvt_pk_bf16_f32 v109, v110, v111
	v_cvt_pk_bf16_f32 v110, v116, v117
	v_cvt_pk_bf16_f32 v111, v118, v119
	s_mov_b32 s65, s64
	v_mov_b64_e32 v[118:119], s[66:67]
	v_mov_b64_e32 v[116:117], s[64:65]
	v_exp_f32_e32 v0, v0
	v_cvt_pk_bf16_f32 v112, v112, v113
	s_setprio 1
	v_mfma_f32_16x16x32_bf16 v[56:59], v[116:119], v[108:111], v[56:59]
	v_cvt_pk_bf16_f32 v113, v114, v115
	v_cvt_pk_bf16_f32 v114, v120, v121
	v_cvt_pk_bf16_f32 v115, v122, v0
	s_nop 1
	v_mfma_f32_16x16x32_bf16 v[56:59], v[116:119], v[112:115], v[56:59]
	s_waitcnt lgkmcnt(7)
	v_mfma_f32_16x16x32_bf16 v[72:75], v[76:79], v[128:131], v[72:75]
	s_movk_i32 s65, 0x400
	v_mfma_f32_16x16x32_bf16 v[48:51], v[76:79], v[108:111], v[48:51]
	s_waitcnt lgkmcnt(6)
	v_mfma_f32_16x16x32_bf16 v[64:67], v[80:83], v[128:131], v[64:67]
	v_mfma_f32_16x16x32_bf16 v[44:47], v[80:83], v[108:111], v[44:47]
	s_waitcnt lgkmcnt(5)
	v_mfma_f32_16x16x32_bf16 v[60:63], v[84:87], v[128:131], v[60:63]
	v_mfma_f32_16x16x32_bf16 v[40:43], v[84:87], v[108:111], v[40:43]
	s_waitcnt lgkmcnt(4)
	v_mfma_f32_16x16x32_bf16 v[52:55], v[88:91], v[128:131], v[52:55]
	v_mfma_f32_16x16x32_bf16 v[36:39], v[88:91], v[108:111], v[36:39]
	s_waitcnt lgkmcnt(3)
	v_mfma_f32_16x16x32_bf16 v[72:75], v[92:95], v[124:127], v[72:75]
	v_mfma_f32_16x16x32_bf16 v[48:51], v[92:95], v[112:115], v[48:51]
	s_waitcnt lgkmcnt(2)
	v_mfma_f32_16x16x32_bf16 v[64:67], v[96:99], v[124:127], v[64:67]
	v_mfma_f32_16x16x32_bf16 v[44:47], v[96:99], v[112:115], v[44:47]
	s_waitcnt lgkmcnt(1)
	v_mfma_f32_16x16x32_bf16 v[60:63], v[100:103], v[124:127], v[60:63]
	v_mfma_f32_16x16x32_bf16 v[40:43], v[100:103], v[112:115], v[40:43]
	s_waitcnt lgkmcnt(0)
	v_mfma_f32_16x16x32_bf16 v[52:55], v[104:107], v[124:127], v[52:55]
	v_mfma_f32_16x16x32_bf16 v[36:39], v[104:107], v[112:115], v[36:39]
	s_setprio 0

.LBB0_1108:
	s_cmp_lt_i32 s2, s7
	s_cselect_b64 s[0:1], -1, 0
	s_cmp_ge_i32 s2, s7
	s_cselect_b64 s[2:3], -1, 0
	s_add_i32 s20, s4, s5
	s_add_i32 s20, s20, -3
	v_cmp_ge_u32_e64 s[58:59], s20, v200
	v_cmp_lt_u32_e32 vcc, s20, v201
	s_and_b64 s[56:57], s[58:59], vcc
	s_or_b64 s[56:57], s[2:3], s[56:57]
	s_and_saveexec_b64 s[2:3], s[56:57]
	s_cbranch_execz .LBB0_1188
	v_add_u32_e32 v0, s87, v202
	v_add_u32_e32 v76, v0, v203
	v_add_u32_e32 v0, v0, v204
	ds_read_b128 v[108:111], v76 offset:17408
	ds_read_b128 v[112:115], v76 offset:19456
	ds_read_b128 v[116:119], v76 offset:21504
	ds_read_b128 v[120:123], v76 offset:23552
	ds_read_b128 v[124:127], v0 offset:17408
	ds_read_b128 v[128:131], v0 offset:19456
	ds_read_b128 v[132:135], v0 offset:21504
	ds_read_b128 v[136:139], v0 offset:23552
	v_add3_u32 v0, s87, v199, v205
	v_add_u32_e32 v92, 0x6000, v0
	v_add_u32_e32 v96, 0x6800, v0
	v_add_u32_e32 v100, 0x7000, v0
	v_add_u32_e32 v0, 0x7800, v0
	ds_read2_b64 v[76:79], v92 offset0:128 offset1:132
	ds_read2_b64 v[80:83], v96 offset0:160 offset1:164
	ds_read2_b64 v[84:87], v100 offset0:192 offset1:196
	ds_read2_b64 v[88:91], v0 offset0:224 offset1:228
	ds_read2_b64 v[92:95], v92 offset0:136 offset1:140
	ds_read2_b64 v[96:99], v96 offset0:168 offset1:172
	ds_read2_b64 v[100:103], v100 offset0:200 offset1:204
	ds_read2_b64 v[104:107], v0 offset0:232 offset1:236
	s_waitcnt lgkmcnt(14)
	s_setprio 1
	v_mfma_f32_16x16x32_bf16 v[140:143], v[108:111], v[4:7], 0
	v_mfma_f32_16x16x32_bf16 v[108:111], v[108:111], v[12:15], 0
	v_mfma_f32_16x16x32_bf16 v[144:147], v[112:115], v[4:7], 0
	v_mfma_f32_16x16x32_bf16 v[112:115], v[112:115], v[12:15], 0
	s_waitcnt lgkmcnt(13)
	v_mfma_f32_16x16x32_bf16 v[148:151], v[116:119], v[4:7], 0
	v_mfma_f32_16x16x32_bf16 v[116:119], v[116:119], v[12:15], 0
	s_waitcnt lgkmcnt(12)
	v_mfma_f32_16x16x32_bf16 v[152:155], v[120:123], v[4:7], 0
	v_mfma_f32_16x16x32_bf16 v[120:123], v[120:123], v[12:15], 0
	s_waitcnt lgkmcnt(11)
	v_mfma_f32_16x16x32_bf16 v[140:143], v[124:127], v[8:11], v[140:143]
	v_mfma_f32_16x16x32_bf16 v[108:111], v[124:127], v[16:19], v[108:111]
	s_waitcnt lgkmcnt(10)
	v_mfma_f32_16x16x32_bf16 v[144:147], v[128:131], v[8:11], v[144:147]
	v_mfma_f32_16x16x32_bf16 v[112:115], v[128:131], v[16:19], v[112:115]
	s_waitcnt lgkmcnt(9)
	v_mfma_f32_16x16x32_bf16 v[148:151], v[132:135], v[8:11], v[148:151]
	v_mfma_f32_16x16x32_bf16 v[116:119], v[132:135], v[16:19], v[116:119]
	s_waitcnt lgkmcnt(8)
	v_mfma_f32_16x16x32_bf16 v[152:155], v[136:139], v[8:11], v[152:155]
	v_mfma_f32_16x16x32_bf16 v[120:123], v[136:139], v[16:19], v[120:123]
	s_setprio 0
	v_cndmask_b32_e64 v0, 0, 1, s[0:1]
	v_cmp_ne_u32_e64 s[56:57], 1, v0
	s_andn2_b64 vcc, exec, s[0:1]
	s_mov_b64 s[0:1], -1
	s_cbranch_vccnz .LBB0_1195
	v_add3_u32 v0, v225, s5, -3
	v_max_i32_e32 v0, -7, v0
	v_add_u32_e32 v0, 7, v0
	v_readlane_b32 s0, v254, 35
	v_min_u32_e32 v0, 14, v0
	v_cmp_lt_u32_e32 vcc, s20, v206
	v_mov_b32_e32 v124, s0
	s_movk_i32 s0, 0x7c
	v_mad_u32_u24 v0, v0, s0, v124
	v_lshl_add_u32 v124, v207, 2, v0
	v_lshl_add_u32 v125, v208, 2, v0
	v_lshl_add_u32 v126, v209, 2, v0
	v_lshl_add_u32 v127, v210, 2, v0
	v_lshl_add_u32 v128, v211, 2, v0
	v_lshl_add_u32 v129, v212, 2, v0
	v_lshl_add_u32 v130, v213, 2, v0
	v_lshl_add_u32 v131, v214, 2, v0
	v_lshl_add_u32 v132, v215, 2, v0
	v_lshl_add_u32 v133, v216, 2, v0
	v_lshl_add_u32 v134, v217, 2, v0
	v_lshl_add_u32 v135, v218, 2, v0
	v_lshl_add_u32 v136, v219, 2, v0
	v_lshl_add_u32 v137, v220, 2, v0
	v_lshl_add_u32 v138, v221, 2, v0
	v_lshl_add_u32 v139, v222, 2, v0
	ds_read_b32 v124, v124 offset:60
	ds_read_b32 v125, v125 offset:60
	ds_read_b32 v126, v126 offset:60
	ds_read_b32 v127, v127 offset:60
	ds_read_b32 v128, v128
	ds_read_b32 v129, v129
	ds_read_b32 v130, v130
	ds_read_b32 v131, v131
	ds_read_b32 v132, v132
	ds_read_b32 v133, v133
	ds_read_b32 v134, v134
	ds_read_b32 v135, v135
	ds_read_b32 v136, v136
	ds_read_b32 v137, v137
	ds_read_b32 v138, v138
	ds_read_b32 v139, v139
	s_and_b64 s[58:59], s[58:59], vcc
	v_mov_b32_e32 v0, 0xff800000
	s_and_b64 s[0:1], s[40:41], s[58:59]
	s_waitcnt lgkmcnt(0)
	v_fmac_f32_e32 v124, 0x3e38aa3b, v140
	v_fmac_f32_e32 v125, 0x3e38aa3b, v141
	v_fmac_f32_e32 v126, 0x3e38aa3b, v142
	v_fmac_f32_e32 v127, 0x3e38aa3b, v143
	v_fmac_f32_e32 v128, 0x3e38aa3b, v144
	v_fmac_f32_e32 v129, 0x3e38aa3b, v145
	v_fmac_f32_e32 v130, 0x3e38aa3b, v146
	v_fmac_f32_e32 v131, 0x3e38aa3b, v147
	v_fmac_f32_e32 v132, 0x3e38aa3b, v148
	v_fmac_f32_e32 v133, 0x3e38aa3b, v149
	v_fmac_f32_e32 v134, 0x3e38aa3b, v150
	v_fmac_f32_e32 v135, 0x3e38aa3b, v151
	v_fmac_f32_e32 v136, 0x3e38aa3b, v152
	v_fmac_f32_e32 v137, 0x3e38aa3b, v153
	v_fmac_f32_e32 v138, 0x3e38aa3b, v154
	v_fmac_f32_e32 v139, 0x3e38aa3b, v155
	s_and_b64 s[66:67], s[42:43], s[58:59]
	v_cndmask_b32_e64 v124, v0, v124, s[0:1]
	s_and_b64 s[0:1], s[44:45], s[58:59]
	v_cndmask_b32_e64 v125, v0, v125, s[66:67]
	s_and_b64 s[66:67], s[46:47], s[58:59]
	v_cndmask_b32_e64 v126, v0, v126, s[0:1]
	s_and_b64 s[0:1], s[90:91], s[58:59]
	v_cndmask_b32_e64 v127, v0, v127, s[66:67]
	s_and_b64 s[66:67], s[8:9], s[58:59]
	v_cndmask_b32_e64 v128, v0, v128, s[0:1]
	s_and_b64 s[0:1], s[88:89], s[58:59]
	v_cndmask_b32_e64 v129, v0, v129, s[66:67]
	s_and_b64 s[66:67], s[94:95], s[58:59]
	v_cndmask_b32_e64 v130, v0, v130, s[0:1]
	s_and_b64 s[0:1], s[96:97], s[58:59]
	v_cndmask_b32_e64 v131, v0, v131, s[66:67]
	s_and_b64 s[66:67], s[84:85], s[58:59]
	v_cndmask_b32_e64 v132, v0, v132, s[0:1]
	s_and_b64 s[0:1], s[18:19], s[58:59]
	v_cndmask_b32_e64 v133, v0, v133, s[66:67]
	s_and_b64 s[66:67], s[62:63], s[58:59]
	v_cndmask_b32_e64 v134, v0, v134, s[0:1]
	s_and_b64 s[0:1], s[48:49], s[58:59]
	v_cndmask_b32_e64 v135, v0, v135, s[66:67]
	s_and_b64 s[66:67], s[50:51], s[58:59]
	v_cndmask_b32_e64 v136, v0, v136, s[0:1]
	s_and_b64 s[0:1], s[52:53], s[58:59]
	v_cndmask_b32_e64 v137, v0, v137, s[66:67]
	s_and_b64 s[66:67], s[54:55], s[58:59]
	v_cndmask_b32_e64 v138, v0, v138, s[0:1]
	s_nop 0
	v_cndmask_b32_e64 v139, v0, v139, s[66:67]
	v_max3_f32 v0, v2, v124, v125
	v_max3_f32 v0, v0, v126, v127
	v_max3_f32 v0, v0, v128, v129
	v_max3_f32 v0, v0, v130, v131
	v_max3_f32 v0, v0, v132, v133
	v_max3_f32 v0, v0, v134, v135
	v_max3_f32 v0, v0, v136, v137
	v_max3_f32 v0, v0, v138, v139

.LBB0_1272:
	s_bitcmp1_b32 s11, 0
	s_cselect_b32 s9, 0x8800, 0
	s_add_i32 s9, s9, 0
	s_add_i32 s11, s6, -3
	v_add_u32_e32 v76, s9, v143
	s_cmp_ge_u32 s11, s5
	v_add3_u32 v0, s9, v146, v147
	v_add_u32_e32 v157, v76, v160
	v_add_u32_e32 v149, v76, v161
	s_cbranch_scc1 .LBB0_1275
	ds_read_b128 v[108:111], v157
	ds_read_b128 v[112:115], v157 offset:2048
	ds_read_b128 v[116:119], v157 offset:4096
	ds_read_b128 v[120:123], v157 offset:6144
	ds_read_b128 v[124:127], v149
	ds_read_b128 v[128:131], v149 offset:2048
	ds_read_b128 v[196:199], v149 offset:4096
	ds_read_b128 v[200:203], v149 offset:6144
	v_add_u32_e32 v92, 0x2000, v0
	v_add_u32_e32 v96, 0x2800, v0
	v_add_u32_e32 v100, 0x3000, v0
	v_add_u32_e32 v104, 0x3800, v0
	ds_read2_b64 v[76:79], v92 offset1:4
	ds_read2_b64 v[80:83], v96 offset0:32 offset1:36
	ds_read2_b64 v[84:87], v100 offset0:64 offset1:68
	ds_read2_b64 v[88:91], v104 offset0:96 offset1:100
	ds_read2_b64 v[92:95], v92 offset0:8 offset1:12
	ds_read2_b64 v[96:99], v96 offset0:40 offset1:44
	ds_read2_b64 v[100:103], v100 offset0:72 offset1:76
	ds_read2_b64 v[104:107], v104 offset0:104 offset1:108
	s_waitcnt lgkmcnt(14)
	s_setprio 1
	v_mfma_f32_16x16x32_bf16 v[132:135], v[108:111], v[12:15], 0
	v_mfma_f32_16x16x32_bf16 v[108:111], v[108:111], v[24:27], 0
	v_mfma_f32_16x16x32_bf16 v[204:207], v[112:115], v[12:15], 0
	v_mfma_f32_16x16x32_bf16 v[112:115], v[112:115], v[24:27], 0
	s_waitcnt lgkmcnt(13)
	v_mfma_f32_16x16x32_bf16 v[208:211], v[116:119], v[12:15], 0
	v_mfma_f32_16x16x32_bf16 v[212:215], v[116:119], v[24:27], 0
	s_waitcnt lgkmcnt(12)
	v_mfma_f32_16x16x32_bf16 v[216:219], v[120:123], v[12:15], 0
	v_mfma_f32_16x16x32_bf16 v[220:223], v[120:123], v[24:27], 0
	s_waitcnt lgkmcnt(11)
	v_mfma_f32_16x16x32_bf16 v[136:139], v[124:127], v[16:19], v[132:135]
	v_mfma_f32_16x16x32_bf16 v[120:123], v[124:127], v[28:31], v[108:111]
	s_waitcnt lgkmcnt(10)
	v_mfma_f32_16x16x32_bf16 v[132:135], v[128:131], v[16:19], v[204:207]
	v_mfma_f32_16x16x32_bf16 v[116:119], v[128:131], v[28:31], v[112:115]
	s_waitcnt lgkmcnt(9)
	v_mfma_f32_16x16x32_bf16 v[128:131], v[196:199], v[16:19], v[208:211]
	v_mfma_f32_16x16x32_bf16 v[112:115], v[196:199], v[28:31], v[212:215]
	s_waitcnt lgkmcnt(8)
	v_mfma_f32_16x16x32_bf16 v[124:127], v[200:203], v[16:19], v[216:219]
	v_mfma_f32_16x16x32_bf16 v[108:111], v[200:203], v[28:31], v[220:223]
	s_setprio 0
	v_max_f32_e32 v158, v137, v137
	v_max_f32_e32 v159, v136, v136
	v_max_f32_e32 v158, v159, v158
	v_max3_f32 v158, v158, v138, v139
	v_max3_f32 v158, v158, v132, v133
	v_max3_f32 v158, v158, v134, v135
	v_max3_f32 v158, v158, v128, v129
	v_max3_f32 v158, v158, v130, v131
	v_max3_f32 v158, v158, v124, v125
	v_max3_f32 v158, v158, v126, v127
	v_mul_f32_e32 v158, 0x3e38aa3b, v158
	v_max_f32_e32 v159, v2, v2
	v_max_f32_e32 v158, v159, v158
	v_cmp_gt_f32_e32 vcc, v158, v2
	s_cbranch_vccz .LBB0_1278
	v_cmp_lt_i32_e32 vcc, v175, v173
	s_nop 1
	v_cndmask_b32_e32 v159, v172, v175, vcc
	v_lshlrev_b32_e32 v159, 2, v159
	ds_bpermute_b32 v159, v159, v158
	v_max_f32_e32 v158, v158, v158
	v_cmp_lt_i32_e32 vcc, v174, v173
	s_waitcnt lgkmcnt(0)
	v_max_f32_e32 v159, v159, v159
	v_max_f32_e32 v158, v158, v159
	v_cndmask_b32_e32 v159, v172, v174, vcc
	v_lshlrev_b32_e32 v159, 2, v159
	ds_bpermute_b32 v159, v159, v158
	s_waitcnt lgkmcnt(0)
	v_max_f32_e32 v159, v159, v159
	v_max_f32_e32 v158, v158, v159
	v_sub_f32_e32 v2, v2, v158
	v_exp_f32_e32 v2, v2
	v_mov_b32_e32 v159, v3
	v_pk_mul_f32 v[74:75], v[74:75], v[2:3] op_sel_hi:[1,0]
	v_pk_mul_f32 v[72:73], v[72:73], v[2:3] op_sel_hi:[1,0]
	v_pk_mul_f32 v[70:71], v[70:71], v[2:3] op_sel_hi:[1,0]
	v_pk_mul_f32 v[68:69], v[68:69], v[2:3] op_sel_hi:[1,0]
	v_pk_mul_f32 v[58:59], v[58:59], v[2:3] op_sel_hi:[1,0]
	v_pk_mul_f32 v[56:57], v[56:57], v[2:3] op_sel_hi:[1,0]
	v_pk_mul_f32 v[54:55], v[54:55], v[2:3] op_sel_hi:[1,0]
	v_pk_mul_f32 v[52:53], v[52:53], v[2:3] op_sel_hi:[1,0]
	v_pk_mul_f32 v[38:39], v[38:39], v[2:3] op_sel_hi:[1,0]
	v_pk_mul_f32 v[36:37], v[36:37], v[2:3] op_sel_hi:[1,0]
	v_mov_b32_e32 v2, v158
	s_branch .LBB0_1279

.LBB0_1276:
	ds_read_b128 v[108:111], v157 offset:17408
	ds_read_b128 v[112:115], v157 offset:19456
	ds_read_b128 v[116:119], v157 offset:21504
	ds_read_b128 v[120:123], v157 offset:23552
	ds_read_b128 v[124:127], v149 offset:17408
	ds_read_b128 v[128:131], v149 offset:19456
	ds_read_b128 v[196:199], v149 offset:21504
	ds_read_b128 v[200:203], v149 offset:23552
	v_add_u32_e32 v92, 0x6000, v0
	v_add_u32_e32 v96, 0x6800, v0
	v_add_u32_e32 v100, 0x7000, v0
	v_add_u32_e32 v0, 0x7800, v0
	ds_read2_b64 v[76:79], v92 offset0:128 offset1:132
	ds_read2_b64 v[80:83], v96 offset0:160 offset1:164
	ds_read2_b64 v[84:87], v100 offset0:192 offset1:196
	ds_read2_b64 v[88:91], v0 offset0:224 offset1:228
	ds_read2_b64 v[92:95], v92 offset0:136 offset1:140
	ds_read2_b64 v[96:99], v96 offset0:168 offset1:172
	ds_read2_b64 v[100:103], v100 offset0:200 offset1:204
	ds_read2_b64 v[104:107], v0 offset0:232 offset1:236
	s_waitcnt lgkmcnt(14)
	s_setprio 1
	v_mfma_f32_16x16x32_bf16 v[132:135], v[108:111], v[12:15], 0
	v_mfma_f32_16x16x32_bf16 v[108:111], v[108:111], v[24:27], 0
	v_mfma_f32_16x16x32_bf16 v[204:207], v[112:115], v[12:15], 0
	v_mfma_f32_16x16x32_bf16 v[112:115], v[112:115], v[24:27], 0
	s_waitcnt lgkmcnt(13)
	v_mfma_f32_16x16x32_bf16 v[208:211], v[116:119], v[12:15], 0
	v_mfma_f32_16x16x32_bf16 v[212:215], v[116:119], v[24:27], 0
	s_waitcnt lgkmcnt(12)
	v_mfma_f32_16x16x32_bf16 v[216:219], v[120:123], v[12:15], 0
	v_mfma_f32_16x16x32_bf16 v[220:223], v[120:123], v[24:27], 0
	s_waitcnt lgkmcnt(11)
	v_mfma_f32_16x16x32_bf16 v[136:139], v[124:127], v[16:19], v[132:135]
	v_mfma_f32_16x16x32_bf16 v[120:123], v[124:127], v[28:31], v[108:111]
	s_waitcnt lgkmcnt(10)
	v_mfma_f32_16x16x32_bf16 v[132:135], v[128:131], v[16:19], v[204:207]
	v_mfma_f32_16x16x32_bf16 v[116:119], v[128:131], v[28:31], v[112:115]
	s_waitcnt lgkmcnt(9)
	v_mfma_f32_16x16x32_bf16 v[128:131], v[196:199], v[16:19], v[208:211]
	v_mfma_f32_16x16x32_bf16 v[112:115], v[196:199], v[28:31], v[212:215]
	s_waitcnt lgkmcnt(8)
	v_mfma_f32_16x16x32_bf16 v[124:127], v[200:203], v[16:19], v[216:219]
	v_mfma_f32_16x16x32_bf16 v[108:111], v[200:203], v[28:31], v[220:223]
	s_setprio 0
	v_max_f32_e32 v0, v137, v137
	v_max_f32_e32 v149, v136, v136
	v_max_f32_e32 v0, v149, v0
	v_max3_f32 v0, v0, v138, v139
	v_max3_f32 v0, v0, v132, v133
	v_max3_f32 v0, v0, v134, v135
	v_max3_f32 v0, v0, v128, v129
	v_max3_f32 v0, v0, v130, v131
	v_max3_f32 v0, v0, v124, v125
	v_max3_f32 v0, v0, v126, v127
	v_mul_f32_e32 v0, 0x3e38aa3b, v0
	v_max_f32_e32 v149, v2, v2
	v_max_f32_e32 v0, v149, v0
	v_cmp_gt_f32_e32 vcc, v0, v2
	s_cbranch_vccz .LBB0_1281
	v_cmp_lt_i32_e32 vcc, v175, v173
	v_mov_b32_e32 v159, v3
	s_nop 0
	v_cndmask_b32_e32 v149, v172, v175, vcc
	v_lshlrev_b32_e32 v149, 2, v149
	ds_bpermute_b32 v149, v149, v0
	v_max_f32_e32 v0, v0, v0
	v_cmp_lt_i32_e32 vcc, v174, v173
	s_waitcnt lgkmcnt(0)
	v_max_f32_e32 v149, v149, v149
	v_max_f32_e32 v0, v0, v149
	v_cndmask_b32_e32 v149, v172, v174, vcc
	v_lshlrev_b32_e32 v149, 2, v149
	ds_bpermute_b32 v149, v149, v0
	s_waitcnt lgkmcnt(0)
	v_max_f32_e32 v149, v149, v149
	v_max_f32_e32 v158, v0, v149
	v_sub_f32_e32 v0, v2, v158
	v_exp_f32_e32 v0, v0
	v_mov_b32_e32 v2, v158
	v_pk_mul_f32 v[74:75], v[74:75], v[0:1] op_sel_hi:[1,0]
	v_pk_mul_f32 v[72:73], v[72:73], v[0:1] op_sel_hi:[1,0]
	v_pk_mul_f32 v[70:71], v[70:71], v[0:1] op_sel_hi:[1,0]
	v_pk_mul_f32 v[68:69], v[68:69], v[0:1] op_sel_hi:[1,0]
	v_pk_mul_f32 v[58:59], v[58:59], v[0:1] op_sel_hi:[1,0]
	v_pk_mul_f32 v[56:57], v[56:57], v[0:1] op_sel_hi:[1,0]
	v_pk_mul_f32 v[54:55], v[54:55], v[0:1] op_sel_hi:[1,0]
	v_pk_mul_f32 v[52:53], v[52:53], v[0:1] op_sel_hi:[1,0]
	v_pk_mul_f32 v[38:39], v[38:39], v[0:1] op_sel_hi:[1,0]
	v_pk_mul_f32 v[36:37], v[36:37], v[0:1] op_sel_hi:[1,0]
	s_branch .LBB0_1282

.LBB0_1285:
	v_fma_f32 v112, v112, s35, -v159
	v_exp_f32_e32 v132, v112
	v_fma_f32 v112, v113, s35, -v159
	v_exp_f32_e32 v133, v112
	v_fma_f32 v112, v114, s35, -v159
	v_exp_f32_e32 v134, v112
	v_fma_f32 v112, v115, s35, -v159
	v_fma_f32 v120, v120, s35, -v159
	v_fma_f32 v121, v121, s35, -v159
	v_fma_f32 v122, v122, s35, -v159
	v_fma_f32 v123, v123, s35, -v159
	v_fma_f32 v116, v116, s35, -v159
	v_fma_f32 v117, v117, s35, -v159
	v_fma_f32 v118, v118, s35, -v159
	v_fma_f32 v119, v119, s35, -v159
	v_exp_f32_e32 v135, v112
	v_mov_b64_e32 v[114:115], s[66:67]
	v_exp_f32_e32 v120, v120
	v_exp_f32_e32 v121, v121
	v_exp_f32_e32 v122, v122
	v_exp_f32_e32 v123, v123
	v_exp_f32_e32 v116, v116
	v_exp_f32_e32 v117, v117
	v_exp_f32_e32 v118, v118
	v_exp_f32_e32 v119, v119
	v_fma_f32 v108, v108, s35, -v159
	v_mov_b64_e32 v[112:113], s[64:65]
	v_exp_f32_e32 v136, v108
	v_fma_f32 v108, v109, s35, -v159
	v_exp_f32_e32 v137, v108
	v_fma_f32 v108, v110, s35, -v159
	v_exp_f32_e32 v138, v108
	v_fma_f32 v108, v111, s35, -v159
	v_exp_f32_e32 v139, v108
	v_cvt_pk_bf16_f32 v108, v120, v121
	v_cvt_pk_bf16_f32 v109, v122, v123
	v_cvt_pk_bf16_f32 v110, v116, v117
	v_cvt_pk_bf16_f32 v111, v118, v119
	v_cvt_pk_bf16_f32 v116, v132, v133
	v_cvt_pk_bf16_f32 v117, v134, v135
	s_setprio 1
	v_mfma_f32_16x16x32_bf16 v[64:67], v[112:115], v[108:111], v[64:67]
	v_cvt_pk_bf16_f32 v118, v136, v137
	v_cvt_pk_bf16_f32 v119, v138, v139
	s_nop 1
	v_mfma_f32_16x16x32_bf16 v[64:67], v[112:115], v[116:119], v[64:67]
	s_waitcnt lgkmcnt(7)
	v_mfma_f32_16x16x32_bf16 v[72:75], v[76:79], v[124:127], v[72:75]
	s_movk_i32 s65, 0x400
	v_mfma_f32_16x16x32_bf16 v[60:63], v[76:79], v[108:111], v[60:63]
	s_waitcnt lgkmcnt(6)
	v_mfma_f32_16x16x32_bf16 v[68:71], v[80:83], v[124:127], v[68:71]
	v_mfma_f32_16x16x32_bf16 v[48:51], v[80:83], v[108:111], v[48:51]
	s_waitcnt lgkmcnt(5)
	v_mfma_f32_16x16x32_bf16 v[56:59], v[84:87], v[124:127], v[56:59]
	v_mfma_f32_16x16x32_bf16 v[44:47], v[84:87], v[108:111], v[44:47]
	s_waitcnt lgkmcnt(4)
	v_mfma_f32_16x16x32_bf16 v[52:55], v[88:91], v[124:127], v[52:55]
	v_mfma_f32_16x16x32_bf16 v[40:43], v[88:91], v[108:111], v[40:43]
	s_waitcnt lgkmcnt(3)
	v_mfma_f32_16x16x32_bf16 v[72:75], v[92:95], v[128:131], v[72:75]
	v_mfma_f32_16x16x32_bf16 v[60:63], v[92:95], v[116:119], v[60:63]
	s_waitcnt lgkmcnt(2)
	v_mfma_f32_16x16x32_bf16 v[68:71], v[96:99], v[128:131], v[68:71]
	v_mfma_f32_16x16x32_bf16 v[48:51], v[96:99], v[116:119], v[48:51]
	s_waitcnt lgkmcnt(1)
	v_mfma_f32_16x16x32_bf16 v[56:59], v[100:103], v[128:131], v[56:59]
	v_mfma_f32_16x16x32_bf16 v[44:47], v[100:103], v[116:119], v[44:47]
	s_waitcnt lgkmcnt(0)
	v_mfma_f32_16x16x32_bf16 v[52:55], v[104:107], v[128:131], v[52:55]
	v_mfma_f32_16x16x32_bf16 v[40:43], v[104:107], v[116:119], v[40:43]
	s_setprio 0
	s_add_i32 s9, s6, -2
	s_cmp_ge_u32 s9, s5
	s_cbranch_scc0 .LBB0_1276

.LBB0_1291:
	v_fma_f32 v112, v112, s35, -v159
	v_fma_f32 v0, v120, s35, -v159
	v_fma_f32 v120, v121, s35, -v159
	v_fma_f32 v121, v122, s35, -v159
	v_fma_f32 v122, v123, s35, -v159
	v_exp_f32_e32 v123, v112
	v_fma_f32 v112, v113, s35, -v159
	v_exp_f32_e32 v132, v112
	v_fma_f32 v112, v114, s35, -v159
	v_exp_f32_e32 v133, v112
	v_fma_f32 v112, v115, s35, -v159
	v_fma_f32 v116, v116, s35, -v159
	v_fma_f32 v117, v117, s35, -v159
	v_fma_f32 v118, v118, s35, -v159
	v_fma_f32 v119, v119, s35, -v159
	v_exp_f32_e32 v134, v112
	v_mov_b64_e32 v[114:115], s[66:67]
	v_exp_f32_e32 v0, v0
	v_exp_f32_e32 v120, v120
	v_exp_f32_e32 v121, v121
	v_exp_f32_e32 v122, v122
	v_exp_f32_e32 v116, v116
	v_exp_f32_e32 v117, v117
	v_exp_f32_e32 v118, v118
	v_exp_f32_e32 v119, v119
	v_fma_f32 v108, v108, s35, -v159
	v_mov_b64_e32 v[112:113], s[64:65]
	v_exp_f32_e32 v135, v108
	v_fma_f32 v108, v109, s35, -v159
	v_exp_f32_e32 v136, v108
	v_fma_f32 v108, v110, s35, -v159
	v_exp_f32_e32 v137, v108
	v_fma_f32 v108, v111, s35, -v159
	v_exp_f32_e32 v138, v108
	v_cvt_pk_bf16_f32 v108, v0, v120
	v_cvt_pk_bf16_f32 v109, v121, v122
	v_cvt_pk_bf16_f32 v110, v116, v117
	v_cvt_pk_bf16_f32 v111, v118, v119
	v_cvt_pk_bf16_f32 v116, v123, v132
	v_cvt_pk_bf16_f32 v117, v133, v134
	s_setprio 1
	v_mfma_f32_16x16x32_bf16 v[64:67], v[112:115], v[108:111], v[64:67]
	v_cvt_pk_bf16_f32 v118, v135, v136
	v_cvt_pk_bf16_f32 v119, v137, v138
	s_nop 1
	v_mfma_f32_16x16x32_bf16 v[64:67], v[112:115], v[116:119], v[64:67]
	s_waitcnt lgkmcnt(7)
	v_mfma_f32_16x16x32_bf16 v[72:75], v[76:79], v[124:127], v[72:75]
	s_movk_i32 s65, 0x400
	v_mfma_f32_16x16x32_bf16 v[60:63], v[76:79], v[108:111], v[60:63]
	s_waitcnt lgkmcnt(6)
	v_mfma_f32_16x16x32_bf16 v[68:71], v[80:83], v[124:127], v[68:71]
	v_mfma_f32_16x16x32_bf16 v[48:51], v[80:83], v[108:111], v[48:51]
	s_waitcnt lgkmcnt(5)
	v_mfma_f32_16x16x32_bf16 v[56:59], v[84:87], v[124:127], v[56:59]
	v_mfma_f32_16x16x32_bf16 v[44:47], v[84:87], v[108:111], v[44:47]
	s_waitcnt lgkmcnt(4)
	v_mfma_f32_16x16x32_bf16 v[52:55], v[88:91], v[124:127], v[52:55]
	v_mfma_f32_16x16x32_bf16 v[40:43], v[88:91], v[108:111], v[40:43]
	s_waitcnt lgkmcnt(3)
	v_mfma_f32_16x16x32_bf16 v[72:75], v[92:95], v[128:131], v[72:75]
	v_mfma_f32_16x16x32_bf16 v[60:63], v[92:95], v[116:119], v[60:63]
	s_waitcnt lgkmcnt(2)
	v_mfma_f32_16x16x32_bf16 v[68:71], v[96:99], v[128:131], v[68:71]
	v_mfma_f32_16x16x32_bf16 v[48:51], v[96:99], v[116:119], v[48:51]
	s_waitcnt lgkmcnt(1)
	v_mfma_f32_16x16x32_bf16 v[56:59], v[100:103], v[128:131], v[56:59]
	v_mfma_f32_16x16x32_bf16 v[44:47], v[100:103], v[116:119], v[44:47]
	s_waitcnt lgkmcnt(0)
	v_mfma_f32_16x16x32_bf16 v[52:55], v[104:107], v[128:131], v[52:55]
	v_mfma_f32_16x16x32_bf16 v[40:43], v[104:107], v[116:119], v[40:43]
	s_setprio 0
	s_andn2_b64 vcc, exec, s[2:3]
	s_cbranch_vccz .LBB0_1287
	s_branch .LBB0_1288
